# DSA: double-buffered K/V LDS stage image (one barrier per stage instead of two)
# baseline (speedup 1.0000x reference)
; #define LAS __attribute__((address_space(3)))
; DI float swap_sum(float m) { auto rr = __builtin_amdgcn_permlane32_swap(__float_as_uint(m), __float_as_uint(m), false, false); return __uint_as_float(rr[0]) + __uint_as_float(rr[1]); }
; DI void dsa_unit(Frame& F, int b, int h, int qb) {
;     const bf16* H0 = (const bf16*)(F.ws + WS_BIG); bf16* O = (bf16*)(F.ws + WS_XB);
;     const unsigned* mask = (const unsigned*)(F.ws + WS_MASK);
;     LAS unsigned char* Ks = F.lds + ATT_K_OFF; LAS unsigned char* Vs = F.lds + ATT_V_OFF;
;     LAS float* tb = (LAS float*)(F.lds + ATT_TB_OFF);
;     const int lane = F.lane, w = F.wave, tl = lane & 31, hf = lane >> 5;
;     const int t0 = 256 * qb, tw = t0 + 32 * w, t = tw + tl;
;     __syncthreads();
;     { const float* bd = (const float*)(F.ws + WS_BIASD) + h * 4096;
;       for (int i = F.tid; i < 4096; i += NTHR) tb[4095 - i] = bd[i]; }
;     bf16x8 qf[4];
;     load_q_frags<64, KSTR64>(F, qf, H0 + (size_t)(b * SEQ + t0) * EVEN_LD + C_QB + h * 64, EVEN_LD, Ks);
;     f32x16 acc[2];
; #pragma unroll
;     for (int e = 0; e < 2; ++e)
; #pragma unroll
;         for (int i = 0; i < 16; ++i) acc[e][i] = 0.f;
;     float S;
;     { float qn = 0.f;
; #pragma unroll
;       for (int st = 0; st < 4; ++st)
; #pragma unroll
;           for (int q = 0; q < 8; ++q) { const float v = __uint_as_float(((unsigned)(unsigned short)qf[st][q]) << 16); qn += v * v; }
;       qn = swap_sum(qn);
;       const float k2 = __uint_as_float(((const unsigned*)(F.ws + WS_KMAX))[b * 16 + h]);
;       const float U = sqrtf(qn * k2) * C_D64 * 1.001f + ((const float*)(F.ws + WS_KMAX + 256))[h] + 0.01f;
;       S = fmaxf(U - 100.f, 0.f); }
;     const bool noshift = __all(S == 0.f);
;     float l = 0.f;
;     const unsigned* mrow = mask + (size_t)(b * SEQ + t) * 128;
;     const int jmax = (t0 + 255) >> 7;
;     RowRegs<64> RK, RV;
;     { const bf16* kg = H0 + (size_t)(b * SEQ) * EVEN_LD + C_KB + h * 64;
;       fetch_rows128<64>(RK, kg, EVEN_LD, F.tid); fetch_rows128<64>(RV, kg + (C_VB - C_KB), EVEN_LD, F.tid); }
;     u32x4 mwn = *(const u32x4*)(mrow);
.LBB0_481:
	s_and_b64 vcc, exec, s[4:5]
	s_cbranch_vccz .LBB0_540
	s_ashr_i32 s0, s84, 31
	s_lshr_b32 s0, s0, 29
	s_add_i32 s0, s84, s0
	s_ashr_i32 s0, s0, 3
	s_lshl_b32 s1, s84, 5
	s_mul_i32 s30, s0, 0xffffff01
	s_add_i32 s30, s30, s1
	s_ashr_i32 s31, s30, 4
	s_and_b32 s33, s0, 15
	s_lshl_b32 s0, s31, 2
	s_ashr_i32 s1, s30, 6
	s_and_b32 s34, s0, 12
	s_lshl_b32 s35, s1, 12
	s_xor_b32 s38, s33, 15
	s_lshl_b32 s36, s1, 4
	s_add_u32 s6, s22, 0x200000
	s_addc_u32 s7, s23, 0
	s_lshl_b32 s39, s82, 5
	s_add_u32 s40, s22, 0x100000
	s_addc_u32 s41, s23, 0
	s_add_u32 s42, s22, 0x1c0000
	s_addc_u32 s43, s23, 0
	s_add_u32 s44, s22, 0x1c0100
	s_mul_i32 s1, s1, 0x3600000
	s_addc_u32 s45, s23, 0
	s_mul_hi_i32 s0, s35, 0x3600
	s_add_u32 s1, s24, s1
	v_lshrrev_b32_e32 v1, 5, v144
	s_addc_u32 s0, s25, s0
	v_lshrrev_b32_e32 v2, 3, v146
	s_waitcnt vmcnt(0)
	v_bfe_u32 v115, v146, 2, 2
	v_lshlrev_b32_e32 v4, 1, v146
	s_add_u32 s46, s1, 0x2000
	v_lshlrev_b32_e32 v160, 2, v1
	v_lshlrev_b32_e32 v114, 4, v1
	v_and_or_b32 v1, v2, 4, v115
	v_and_b32_e32 v116, 32, v4
	v_lshlrev_b32_e32 v4, 3, v146
	s_movk_i32 s48, 0x90
	s_addc_u32 s47, s0, 0
	v_mul_u32_u24_e32 v104, 0x3600, v2
	v_add_u32_e32 v117, 0x200, v146
	v_and_b32_e32 v118, 24, v4
	v_mul_u32_u24_e32 v121, 0x90, v1
	v_mad_u32_u24 v1, v2, s48, 0
	v_xor_b32_e32 v2, 0xfff, v146
	s_add_i32 s4, 0, 0x12000
	v_xor_b32_e32 v4, 0xbff, v146
	v_xor_b32_e32 v6, 0x7ff, v146
	v_and_b32_e32 v159, 31, v146
	v_lshrrev_b32_e32 v3, 3, v117
	s_add_i32 s3, s3, 0
	v_lshl_add_u32 v122, v2, 2, s4
	v_sub_u32_e32 v2, 0xdff, v146
	v_lshl_add_u32 v124, v4, 2, s4
	v_sub_u32_e32 v4, 0x9ff, v146
	v_lshl_add_u32 v126, v6, 2, s4
	v_sub_u32_e32 v6, 0x5ff, v146
	s_waitcnt lgkmcnt(7)
	v_xor_b32_e32 v8, 0x3ff, v146
	s_or_b32 s49, s35, 0x80
	v_mov_b32_e32 v107, 0
	v_lshlrev_b32_e32 v0, 3, v147
	v_mul_u32_u24_e32 v108, 0x3600, v3
	v_add_u32_e32 v119, 0, v114
	v_mul_u32_u24_e32 v5, 0x90, v159
	v_lshlrev_b32_e32 v7, 4, v147
	v_mad_u32_u24 v3, v3, s48, 0
	v_lshl_add_u32 v123, v2, 2, s4
	v_or_b32_e32 v2, 0x400, v146
	v_lshl_add_u32 v125, v4, 2, s4
	v_or_b32_e32 v4, 0x800, v146
	v_lshl_add_u32 v127, v6, 2, s4
	v_or_b32_e32 v6, 0xc00, v146
	v_lshl_add_u32 v128, v8, 2, s4
	s_movk_i32 s0, 0xe00
	v_sub_u32_e32 v8, 0x1ff, v146
	s_add_u32 s10, s22, 0x200010
	s_movk_i32 s37, 0x3600
	v_mov_b32_e32 v105, v107
	v_mov_b32_e32 v109, v107
	s_mov_b32 s9, 0
	v_add3_u32 v120, 0, v116, v118
	v_cmp_gt_u32_e64 s[0:1], s0, v6
	v_lshl_add_u32 v129, v8, 2, s4
	s_addc_u32 s11, s23, 0
	v_or_b32_e32 v130, s39, v159
	v_lshlrev_b32_e32 v110, 2, v146
	v_mov_b32_e32 v111, v107
	v_lshlrev_b32_e32 v131, 2, v2
	s_movk_i32 s50, 0x1000
	v_lshlrev_b32_e32 v132, 2, v4
	v_lshlrev_b32_e32 v133, 2, v6
	s_mov_b32 s51, 0xf800000
	v_mov_b32_e32 v134, 0x260
	v_lshlrev_b32_e32 v106, 1, v0
	v_add_u32_e32 v135, v1, v7
	v_add_u32_e32 v136, v3, v7
	s_mov_b32 s52, 0xff800000
	v_add_u32_e32 v137, v119, v5
	s_mov_b32 s53, 0
	s_mov_b32 s101, 0
	s_branch .LBB0_484

; DI void dsa_unit(Frame& F, int b, int h, int qb) {
;     ...
;     for (int j = 0; j <= jmax; ++j) {
;         __syncthreads();
;         put_rows128<64, KSTR64>(Ks, RK, F.tid); put_rows128<64, VSTR64>(Vs, RV, F.tid);
;         const u32x4 mw4 = mwn;
;         __syncthreads();
.LBB0_493:
	s_and_b32 s100, s59, 1
	s_mul_i32 s100, s100, 0x4800
	s_sub_i32 s98, s100, s101
	s_mov_b32 s101, s100
	v_add_u32_e32 v135, s98, v135
	v_add_u32_e32 v136, s98, v136
	v_add_u32_e32 v137, s98, v137
	v_add_u32_e32 v121, s98, v121
	s_bitcmp1_b32 s59, 0
	s_cbranch_scc1 .Ldsa_top_b
	s_cmp_gt_u32 s59, s54
	s_cbranch_scc1 .Ldsa_wa0
	s_waitcnt vmcnt(5)
	s_branch .Ldsa_wa1

; #define LAS __attribute__((address_space(3)))
; DI void sb_unit(Frame& F, int b, int h, int qb) {
;     const bf16* H0 = (const bf16*)(F.ws + WS_BIG); bf16* O = (bf16*)(F.ws + WS_XB);
;     LAS unsigned char* Ks = F.lds + ATT_K_OFF; LAS unsigned char* Vs = F.lds + ATT_V_OFF;
;     volatile LAS int* flags = (volatile LAS int*)(F.lds + ATT_FLAG_OFF);
;     const int lane = F.lane, w = F.wave, tl = lane & 31, hf = lane >> 5;
;     const int t0 = 256 * qb, tw = t0 + 32 * w, t = tw + tl;
;     __syncthreads();
;     if (F.tid < 8) flags[F.tid] = 0;
;     bf16x8 qf[8];
;     load_q_frags<128, KSTR128>(F, qf, H0 + (size_t)(b * SEQ + t0) * EVEN_LD + C_QA + h * 128, EVEN_LD, Ks);
;     f32x16 acc[4];
; #pragma unroll
;     for (int e = 0; e < 4; ++e)
; #pragma unroll
;         for (int i = 0; i < 16; ++i) acc[e][i] = 0.f;
;     float carry = 0.f; bool wdone = false;
;     RowRegs<128> RK, RV;
;     const int jtop = (t0 + 255) >> 7;
;     { const bf16* kg = H0 + (size_t)(b * SEQ + 128 * jtop) * EVEN_LD + C_KA + h * 128;
;       fetch_rows128<128>(RK, kg, EVEN_LD, F.tid); fetch_rows128<128>(RV, kg + (C_VA - C_KA), EVEN_LD, F.tid); }
.LBB0_521:
	s_sub_i32 s98, 0, s101
	s_mov_b32 s101, 0
	v_add_u32_e32 v135, s98, v135
	v_add_u32_e32 v136, s98, v136
	v_add_u32_e32 v137, s98, v137
	v_add_u32_e32 v121, s98, v121
	s_nop 0
	v_lshrrev_b32_e32 v7, 4, v146
	s_add_i32 s41, 0, 0x16000
	v_or_b32_e32 v9, 64, v7
	s_lshl_b32 s8, s82, 2
	s_movk_i32 s43, 0x110
	v_mul_u32_u24_e32 v8, 0x1b00, v7
	s_add_i32 s42, s41, s8
	v_mad_u32_u24 v161, v7, s43, 0
	v_lshlrev_b32_e32 v7, 4, v9
	s_movk_i32 s8, 0x4400
	v_add_u32_e32 v1, 0x600, v146
	v_lshrrev_b32_e32 v10, 4, v117
	v_add3_u32 v7, v161, v7, s8
	s_mul_i32 s8, s82, 0x2200
	s_lshl_b32 s0, s31, 8
	v_lshrrev_b32_e32 v3, 4, v1
	v_and_b32_e32 v5, 15, v146
	v_mul_u32_u24_e32 v4, 0x1b00, v9
	v_mul_u32_u24_e32 v6, 0x1b00, v10
	v_mad_u32_u24 v163, v10, s43, 0
	s_add_i32 s44, s8, 0
	v_bfe_u32 v9, v146, 5, 1
	v_mul_u32_u24_e32 v10, 0x120, v115
	s_movk_i32 s8, 0x480
	s_and_b32 s3, s0, 0x300
	s_lshl_b32 s0, s30, 6
	v_mul_u32_u24_e32 v0, 0x1b00, v3
	v_lshlrev_b32_e32 v2, 3, v5
	v_lshlrev_b32_e32 v162, 4, v5
	v_mad_u32_u24 v164, v3, s43, 0
	v_and_b32_e32 v3, 0x3f0, v146
	v_and_b32_e32 v5, 0x7f0, v117
	v_and_b32_e32 v1, 0xff0, v1
	v_mad_u32_u24 v9, v9, s8, v10
	s_and_b32 s17, s0, 0xfffff000
	v_add_u32_e32 v3, v161, v3
	v_add_u32_e32 v5, v163, v5
	v_add_u32_e32 v1, v164, v1
	v_add3_u32 v165, v9, v116, v118
	v_mul_u32_u24_e32 v9, 0x110, v159
	s_movk_i32 s8, 0x6600
	s_add_i32 s40, s17, 0xffffff80
	v_cmp_gt_u32_e64 s[0:1], 8, v146
	s_mov_b32 s13, 0
	v_lshl_add_u32 v147, v146, 2, s41
	v_mov_b32_e32 v149, 0
	v_cmp_gt_u32_e64 s[4:5], 32, v144
	v_cmp_eq_u32_e64 s[6:7], 0, v144
	v_add3_u32 v166, v9, v114, s8
	s_mov_b64 s[8:9], -1
	s_movk_i32 s45, 0x3600
	v_lshlrev_b32_e32 v150, 1, v0
	v_lshlrev_b32_e32 v152, 1, v2
	v_lshlrev_b32_e32 v154, 1, v4
	v_lshlrev_b32_e32 v156, 1, v6
	v_lshlrev_b32_e32 v148, 1, v8
	s_add_i32 s46, 0, 0x16004
	s_add_i32 s47, 0, 0x16008
	s_add_i32 s48, 0, 0x1600c
	s_add_i32 s49, 0, 0x16010
	s_add_i32 s50, 0, 0x16014
	s_add_i32 s51, 0, 0x16018
	s_add_i32 s52, 0, 0x1601c
	v_add_u32_e32 v167, v3, v162
	v_add_u32_e32 v168, v5, v162
	v_add_u32_e32 v169, v7, v162
	v_add_u32_e32 v170, v1, v162
	s_mov_b32 s16, 0x3e0293ee
	s_mov_b32 s53, 0xbe0293ee
	s_mov_b32 s54, 0xc3480000
	v_mov_b32_e32 v171, 1
	v_mov_b32_e32 v172, 0xf149f2ca
	s_mov_b32 s12, 0
	s_branch .LBB0_523
